# accumulator zeroing per unit with 64 v_mov_b64 instead of 127 v_mov_b32
# speedup vs baseline: 1.0109x; 1.0002x over previous
.LBB0_91:
	s_ashr_i32 s53, s52, 31
	s_lshl_b64 s[10:11], s[52:53], 19
	s_add_u32 s54, s68, s10
	s_addc_u32 s55, s69, s11
	s_and_b64 s[10:11], s[40:41], exec
	s_cselect_b32 s5, s55, s7
	s_cselect_b32 s24, s54, s6
	s_ashr_i32 s51, s50, 31
	s_lshl_b64 s[10:11], s[50:51], 19
	s_add_u32 s56, s15, s10
	s_addc_u32 s57, s26, s11
	s_and_b64 s[10:11], s[40:41], exec
	s_cselect_b32 s47, s57, s9
	s_cselect_b32 s51, s56, s8
	s_add_u32 s6, s6, 0x40080
	s_addc_u32 s7, s7, 0
	s_add_u32 s53, s8, 0x100
	v_mov_b32_e32 v0, 0
	v_mov_b32_e32 v251, 0x260
	v_mov_b32_e32 v224, 0x3e124925
	v_mov_b32_e32 v223, 0x3e2aaaab
	v_mov_b32_e32 v222, 0x3e4ccccd
	v_mov_b32_e32 v221, 0x3e800000
	v_mov_b32_e32 v220, 0x3eaaaaab
	s_addc_u32 s58, s9, 0
	s_mov_b32 s59, -2
	v_mov_b32_e32 v1, v0
	v_mov_b64_e32 v[2:3], 0
	v_mov_b64_e32 v[4:5], 0
	v_mov_b64_e32 v[6:7], 0
	v_mov_b64_e32 v[8:9], 0
	v_mov_b64_e32 v[10:11], 0
	v_mov_b64_e32 v[12:13], 0
	v_mov_b64_e32 v[14:15], 0
	v_mov_b64_e32 v[16:17], 0
	v_mov_b64_e32 v[18:19], 0
	v_mov_b64_e32 v[20:21], 0
	v_mov_b64_e32 v[22:23], 0
	v_mov_b64_e32 v[24:25], 0
	v_mov_b64_e32 v[26:27], 0
	v_mov_b64_e32 v[28:29], 0
	v_mov_b64_e32 v[30:31], 0
	v_mov_b64_e32 v[32:33], 0
	v_mov_b64_e32 v[34:35], 0
	v_mov_b64_e32 v[36:37], 0
	v_mov_b64_e32 v[38:39], 0
	v_mov_b64_e32 v[40:41], 0
	v_mov_b64_e32 v[42:43], 0
	v_mov_b64_e32 v[44:45], 0
	v_mov_b64_e32 v[46:47], 0
	v_mov_b64_e32 v[48:49], 0
	v_mov_b64_e32 v[50:51], 0
	v_mov_b64_e32 v[52:53], 0
	v_mov_b64_e32 v[54:55], 0
	v_mov_b64_e32 v[56:57], 0
	v_mov_b64_e32 v[58:59], 0
	v_mov_b64_e32 v[60:61], 0
	v_mov_b64_e32 v[62:63], 0
	v_mov_b64_e32 v[64:65], 0
	v_mov_b64_e32 v[66:67], 0
	v_mov_b64_e32 v[68:69], 0
	v_mov_b64_e32 v[70:71], 0
	v_mov_b64_e32 v[72:73], 0
	v_mov_b64_e32 v[74:75], 0
	v_mov_b64_e32 v[76:77], 0
	v_mov_b64_e32 v[78:79], 0
	v_mov_b64_e32 v[80:81], 0
	v_mov_b64_e32 v[82:83], 0
	v_mov_b64_e32 v[84:85], 0
	v_mov_b64_e32 v[86:87], 0
	v_mov_b64_e32 v[88:89], 0
	v_mov_b64_e32 v[90:91], 0
	v_mov_b64_e32 v[92:93], 0
	v_mov_b64_e32 v[94:95], 0
	v_mov_b64_e32 v[96:97], 0
	v_mov_b64_e32 v[98:99], 0
	v_mov_b64_e32 v[100:101], 0
	v_mov_b64_e32 v[102:103], 0
	v_mov_b64_e32 v[104:105], 0
	v_mov_b64_e32 v[106:107], 0
	v_mov_b64_e32 v[108:109], 0
	v_mov_b64_e32 v[110:111], 0
	v_mov_b64_e32 v[112:113], 0
	v_mov_b64_e32 v[114:115], 0
	v_mov_b64_e32 v[116:117], 0
	v_mov_b64_e32 v[118:119], 0
	v_mov_b64_e32 v[120:121], 0
	v_mov_b64_e32 v[122:123], 0
	v_mov_b64_e32 v[124:125], 0
	v_mov_b64_e32 v[126:127], 0

.LBB0_146:
	s_ashr_i32 s55, s54, 31
	s_lshl_b64 s[10:11], s[54:55], 19
	s_add_u32 s56, s86, s10
	s_addc_u32 s57, s87, s11
	s_and_b64 s[10:11], s[40:41], exec
	s_cselect_b32 s24, s57, s7
	s_cselect_b32 s38, s56, s6
	s_ashr_i32 s58, s54, 4
	s_ashr_i32 s53, s52, 31
	s_ashr_i32 s59, s58, 31
	s_lshl_b64 s[10:11], s[52:53], 19
	s_lshl_b64 s[58:59], s[58:59], 21
	s_add_u32 s10, s16, s10
	s_addc_u32 s11, s17, s11
	s_add_u32 s58, s10, s58
	s_addc_u32 s59, s11, s59
	s_and_b64 s[10:11], s[40:41], exec
	s_cselect_b32 s53, s59, s9
	s_cselect_b32 s55, s58, s8
	s_add_u32 s6, s6, 0x40080
	s_addc_u32 s7, s7, 0
	s_add_u32 s60, s8, 0x100
	v_mov_b32_e32 v0, 0
	v_mov_b32_e32 v251, 0x260
	v_mov_b32_e32 v220, 0x3e124925
	v_mov_b32_e32 v219, 0x3e2aaaab
	v_mov_b32_e32 v218, 0x3e4ccccd
	v_mov_b32_e32 v217, 0x3e800000
	v_mov_b32_e32 v216, 0x3eaaaaab
	s_addc_u32 s61, s9, 0
	s_mov_b32 s74, -2
	v_mov_b32_e32 v1, v0
	v_mov_b64_e32 v[2:3], 0
	v_mov_b64_e32 v[4:5], 0
	v_mov_b64_e32 v[6:7], 0
	v_mov_b64_e32 v[8:9], 0
	v_mov_b64_e32 v[10:11], 0
	v_mov_b64_e32 v[12:13], 0
	v_mov_b64_e32 v[14:15], 0
	v_mov_b64_e32 v[16:17], 0
	v_mov_b64_e32 v[18:19], 0
	v_mov_b64_e32 v[20:21], 0
	v_mov_b64_e32 v[22:23], 0
	v_mov_b64_e32 v[24:25], 0
	v_mov_b64_e32 v[26:27], 0
	v_mov_b64_e32 v[28:29], 0
	v_mov_b64_e32 v[30:31], 0
	v_mov_b64_e32 v[32:33], 0
	v_mov_b64_e32 v[34:35], 0
	v_mov_b64_e32 v[36:37], 0
	v_mov_b64_e32 v[38:39], 0
	v_mov_b64_e32 v[40:41], 0
	v_mov_b64_e32 v[42:43], 0
	v_mov_b64_e32 v[44:45], 0
	v_mov_b64_e32 v[46:47], 0
	v_mov_b64_e32 v[48:49], 0
	v_mov_b64_e32 v[50:51], 0
	v_mov_b64_e32 v[52:53], 0
	v_mov_b64_e32 v[54:55], 0
	v_mov_b64_e32 v[56:57], 0
	v_mov_b64_e32 v[58:59], 0
	v_mov_b64_e32 v[60:61], 0
	v_mov_b64_e32 v[62:63], 0
	v_mov_b64_e32 v[64:65], 0
	v_mov_b64_e32 v[66:67], 0
	v_mov_b64_e32 v[68:69], 0
	v_mov_b64_e32 v[70:71], 0
	v_mov_b64_e32 v[72:73], 0
	v_mov_b64_e32 v[74:75], 0
	v_mov_b64_e32 v[76:77], 0
	v_mov_b64_e32 v[78:79], 0
	v_mov_b64_e32 v[80:81], 0
	v_mov_b64_e32 v[82:83], 0
	v_mov_b64_e32 v[84:85], 0
	v_mov_b64_e32 v[86:87], 0
	v_mov_b64_e32 v[88:89], 0
	v_mov_b64_e32 v[90:91], 0
	v_mov_b64_e32 v[92:93], 0
	v_mov_b64_e32 v[94:95], 0
	v_mov_b64_e32 v[96:97], 0
	v_mov_b64_e32 v[98:99], 0
	v_mov_b64_e32 v[100:101], 0
	v_mov_b64_e32 v[102:103], 0
	v_mov_b64_e32 v[104:105], 0
	v_mov_b64_e32 v[106:107], 0
	v_mov_b64_e32 v[108:109], 0
	v_mov_b64_e32 v[110:111], 0
	v_mov_b64_e32 v[112:113], 0
	v_mov_b64_e32 v[114:115], 0
	v_mov_b64_e32 v[116:117], 0
	v_mov_b64_e32 v[118:119], 0
	v_mov_b64_e32 v[120:121], 0
	v_mov_b64_e32 v[122:123], 0
	v_mov_b64_e32 v[124:125], 0
	v_mov_b64_e32 v[126:127], 0

.LBB0_233:
	s_ashr_i32 s53, s52, 31
	s_lshl_b64 s[4:5], s[52:53], 19
	s_add_u32 s54, s68, s4
	s_addc_u32 s55, s69, s5
	s_and_b64 s[4:5], s[40:41], exec
	s_cselect_b32 s4, s55, s7
	s_cselect_b32 s5, s54, s6
	s_ashr_i32 s42, s52, 4
	s_ashr_i32 s51, s50, 31
	s_ashr_i32 s43, s42, 31
	s_lshl_b64 s[10:11], s[50:51], 19
	s_lshl_b64 s[42:43], s[42:43], 21
	s_add_u32 s10, s81, s10
	s_addc_u32 s11, s25, s11
	s_add_u32 s56, s10, s42
	s_addc_u32 s57, s11, s43
	s_and_b64 s[10:11], s[40:41], exec
	s_cselect_b32 s24, s57, s9
	s_cselect_b32 s42, s56, s8
	s_add_u32 s6, s6, 0x40080
	s_addc_u32 s7, s7, 0
	s_add_u32 s43, s8, 0x100
	v_mov_b32_e32 v0, 0
	v_mov_b32_e32 v251, 0x260
	v_mov_b32_e32 v222, 0x3e124925
	v_mov_b32_e32 v221, 0x3e2aaaab
	v_mov_b32_e32 v220, 0x3e4ccccd
	v_mov_b32_e32 v219, 0x3e800000
	v_mov_b32_e32 v218, 0x3eaaaaab
	s_addc_u32 s51, s9, 0
	s_mov_b32 s53, -2
	v_mov_b32_e32 v1, v0
	v_mov_b64_e32 v[2:3], 0
	v_mov_b64_e32 v[4:5], 0
	v_mov_b64_e32 v[6:7], 0
	v_mov_b64_e32 v[8:9], 0
	v_mov_b64_e32 v[10:11], 0
	v_mov_b64_e32 v[12:13], 0
	v_mov_b64_e32 v[14:15], 0
	v_mov_b64_e32 v[16:17], 0
	v_mov_b64_e32 v[18:19], 0
	v_mov_b64_e32 v[20:21], 0
	v_mov_b64_e32 v[22:23], 0
	v_mov_b64_e32 v[24:25], 0
	v_mov_b64_e32 v[26:27], 0
	v_mov_b64_e32 v[28:29], 0
	v_mov_b64_e32 v[30:31], 0
	v_mov_b64_e32 v[32:33], 0
	v_mov_b64_e32 v[34:35], 0
	v_mov_b64_e32 v[36:37], 0
	v_mov_b64_e32 v[38:39], 0
	v_mov_b64_e32 v[40:41], 0
	v_mov_b64_e32 v[42:43], 0
	v_mov_b64_e32 v[44:45], 0
	v_mov_b64_e32 v[46:47], 0
	v_mov_b64_e32 v[48:49], 0
	v_mov_b64_e32 v[50:51], 0
	v_mov_b64_e32 v[52:53], 0
	v_mov_b64_e32 v[54:55], 0
	v_mov_b64_e32 v[56:57], 0
	v_mov_b64_e32 v[58:59], 0
	v_mov_b64_e32 v[60:61], 0
	v_mov_b64_e32 v[62:63], 0
	v_mov_b64_e32 v[64:65], 0
	v_mov_b64_e32 v[66:67], 0
	v_mov_b64_e32 v[68:69], 0
	v_mov_b64_e32 v[70:71], 0
	v_mov_b64_e32 v[72:73], 0
	v_mov_b64_e32 v[74:75], 0
	v_mov_b64_e32 v[76:77], 0
	v_mov_b64_e32 v[78:79], 0
	v_mov_b64_e32 v[80:81], 0
	v_mov_b64_e32 v[82:83], 0
	v_mov_b64_e32 v[84:85], 0
	v_mov_b64_e32 v[86:87], 0
	v_mov_b64_e32 v[88:89], 0
	v_mov_b64_e32 v[90:91], 0
	v_mov_b64_e32 v[92:93], 0
	v_mov_b64_e32 v[94:95], 0
	v_mov_b64_e32 v[96:97], 0
	v_mov_b64_e32 v[98:99], 0
	v_mov_b64_e32 v[100:101], 0
	v_mov_b64_e32 v[102:103], 0
	v_mov_b64_e32 v[104:105], 0
	v_mov_b64_e32 v[106:107], 0
	v_mov_b64_e32 v[108:109], 0
	v_mov_b64_e32 v[110:111], 0
	v_mov_b64_e32 v[112:113], 0
	v_mov_b64_e32 v[114:115], 0
	v_mov_b64_e32 v[116:117], 0
	v_mov_b64_e32 v[118:119], 0
	v_mov_b64_e32 v[120:121], 0
	v_mov_b64_e32 v[122:123], 0
	v_mov_b64_e32 v[124:125], 0
	v_mov_b64_e32 v[126:127], 0

.LBB0_332:
	s_add_u32 s24, s6, 0x100
	s_addc_u32 s38, s7, 0
	s_add_u32 s6, s8, 0x8000
	v_mov_b32_e32 v0, 0
	s_addc_u32 s7, s9, 0
	s_mov_b32 s8, 0
	v_mov_b32_e32 v1, v0
	v_mov_b64_e32 v[2:3], 0
	v_mov_b64_e32 v[4:5], 0
	v_mov_b64_e32 v[6:7], 0
	v_mov_b64_e32 v[8:9], 0
	v_mov_b64_e32 v[10:11], 0
	v_mov_b64_e32 v[12:13], 0
	v_mov_b64_e32 v[14:15], 0
	v_mov_b64_e32 v[16:17], 0
	v_mov_b64_e32 v[18:19], 0
	v_mov_b64_e32 v[20:21], 0
	v_mov_b64_e32 v[22:23], 0
	v_mov_b64_e32 v[24:25], 0
	v_mov_b64_e32 v[26:27], 0
	v_mov_b64_e32 v[28:29], 0
	v_mov_b64_e32 v[30:31], 0
	v_mov_b64_e32 v[32:33], 0
	v_mov_b64_e32 v[34:35], 0
	v_mov_b64_e32 v[36:37], 0
	v_mov_b64_e32 v[38:39], 0
	v_mov_b64_e32 v[40:41], 0
	v_mov_b64_e32 v[42:43], 0
	v_mov_b64_e32 v[44:45], 0
	v_mov_b64_e32 v[46:47], 0
	v_mov_b64_e32 v[48:49], 0
	v_mov_b64_e32 v[50:51], 0
	v_mov_b64_e32 v[52:53], 0
	v_mov_b64_e32 v[54:55], 0
	v_mov_b64_e32 v[56:57], 0
	v_mov_b64_e32 v[58:59], 0
	v_mov_b64_e32 v[60:61], 0
	v_mov_b64_e32 v[62:63], 0
	v_mov_b64_e32 v[64:65], 0
	v_mov_b64_e32 v[66:67], 0
	v_mov_b64_e32 v[68:69], 0
	v_mov_b64_e32 v[70:71], 0
	v_mov_b64_e32 v[72:73], 0
	v_mov_b64_e32 v[74:75], 0
	v_mov_b64_e32 v[76:77], 0
	v_mov_b64_e32 v[78:79], 0
	v_mov_b64_e32 v[80:81], 0
	v_mov_b64_e32 v[82:83], 0
	v_mov_b64_e32 v[84:85], 0
	v_mov_b64_e32 v[86:87], 0
	v_mov_b64_e32 v[88:89], 0
	v_mov_b64_e32 v[90:91], 0
	v_mov_b64_e32 v[92:93], 0
	v_mov_b64_e32 v[94:95], 0
	v_mov_b64_e32 v[96:97], 0
	v_mov_b64_e32 v[98:99], 0
	v_mov_b64_e32 v[100:101], 0
	v_mov_b64_e32 v[102:103], 0
	v_mov_b64_e32 v[104:105], 0
	v_mov_b64_e32 v[106:107], 0
	v_mov_b64_e32 v[108:109], 0
	v_mov_b64_e32 v[110:111], 0
	v_mov_b64_e32 v[112:113], 0
	v_mov_b64_e32 v[114:115], 0
	v_mov_b64_e32 v[116:117], 0
	v_mov_b64_e32 v[118:119], 0
	v_mov_b64_e32 v[120:121], 0
	v_mov_b64_e32 v[122:123], 0
	v_mov_b64_e32 v[124:125], 0
	v_mov_b64_e32 v[126:127], 0

.LBB0_374:
	s_add_u32 s6, s6, 0x80
	s_addc_u32 s7, s7, 0
	s_add_u32 s10, s8, 0x100
	v_mov_b32_e32 v0, 0
	s_addc_u32 s11, s9, 0
	s_mov_b32 s8, 0
	v_mov_b32_e32 v1, v0
	v_mov_b64_e32 v[2:3], 0
	v_mov_b64_e32 v[4:5], 0
	v_mov_b64_e32 v[6:7], 0
	v_mov_b64_e32 v[8:9], 0
	v_mov_b64_e32 v[10:11], 0
	v_mov_b64_e32 v[12:13], 0
	v_mov_b64_e32 v[14:15], 0
	v_mov_b64_e32 v[16:17], 0
	v_mov_b64_e32 v[18:19], 0
	v_mov_b64_e32 v[20:21], 0
	v_mov_b64_e32 v[22:23], 0
	v_mov_b64_e32 v[24:25], 0
	v_mov_b64_e32 v[26:27], 0
	v_mov_b64_e32 v[28:29], 0
	v_mov_b64_e32 v[30:31], 0
	v_mov_b64_e32 v[32:33], 0
	v_mov_b64_e32 v[34:35], 0
	v_mov_b64_e32 v[36:37], 0
	v_mov_b64_e32 v[38:39], 0
	v_mov_b64_e32 v[40:41], 0
	v_mov_b64_e32 v[42:43], 0
	v_mov_b64_e32 v[44:45], 0
	v_mov_b64_e32 v[46:47], 0
	v_mov_b64_e32 v[48:49], 0
	v_mov_b64_e32 v[50:51], 0
	v_mov_b64_e32 v[52:53], 0
	v_mov_b64_e32 v[54:55], 0
	v_mov_b64_e32 v[56:57], 0
	v_mov_b64_e32 v[58:59], 0
	v_mov_b64_e32 v[60:61], 0
	v_mov_b64_e32 v[62:63], 0
	v_mov_b64_e32 v[64:65], 0
	v_mov_b64_e32 v[66:67], 0
	v_mov_b64_e32 v[68:69], 0
	v_mov_b64_e32 v[70:71], 0
	v_mov_b64_e32 v[72:73], 0
	v_mov_b64_e32 v[74:75], 0
	v_mov_b64_e32 v[76:77], 0
	v_mov_b64_e32 v[78:79], 0
	v_mov_b64_e32 v[80:81], 0
	v_mov_b64_e32 v[82:83], 0
	v_mov_b64_e32 v[84:85], 0
	v_mov_b64_e32 v[86:87], 0
	v_mov_b64_e32 v[88:89], 0
	v_mov_b64_e32 v[90:91], 0
	v_mov_b64_e32 v[92:93], 0
	v_mov_b64_e32 v[94:95], 0
	v_mov_b64_e32 v[96:97], 0
	v_mov_b64_e32 v[98:99], 0
	v_mov_b64_e32 v[100:101], 0
	v_mov_b64_e32 v[102:103], 0
	v_mov_b64_e32 v[104:105], 0
	v_mov_b64_e32 v[106:107], 0
	v_mov_b64_e32 v[108:109], 0
	v_mov_b64_e32 v[110:111], 0
	v_mov_b64_e32 v[112:113], 0
	v_mov_b64_e32 v[114:115], 0
	v_mov_b64_e32 v[116:117], 0
	v_mov_b64_e32 v[118:119], 0
	v_mov_b64_e32 v[120:121], 0
	v_mov_b64_e32 v[122:123], 0
	v_mov_b64_e32 v[124:125], 0
	v_mov_b64_e32 v[126:127], 0

.LBB0_551:
	s_ashr_i32 s51, s50, 31
	s_lshl_b64 s[4:5], s[50:51], 19
	s_add_u32 s52, s68, s4
	s_addc_u32 s53, s69, s5
	s_and_b64 s[4:5], s[40:41], exec
	s_cselect_b32 s4, s53, s7
	s_cselect_b32 s5, s52, s6
	s_ashr_i32 s47, s46, 31
	s_lshl_b64 s[10:11], s[46:47], 19
	s_add_u32 s54, s13, s10
	s_addc_u32 s55, s15, s11
	s_and_b64 s[10:11], s[40:41], exec
	s_cselect_b32 s24, s55, s9
	s_cselect_b32 s38, s54, s8
	s_add_u32 s6, s6, 0x40080
	s_addc_u32 s7, s7, 0
	s_add_u32 s47, s8, 0x100
	v_mov_b32_e32 v0, 0
	s_addc_u32 s51, s9, 0
	s_mov_b32 s56, -2
	v_mov_b32_e32 v1, v0
	v_mov_b64_e32 v[2:3], 0
	v_mov_b64_e32 v[4:5], 0
	v_mov_b64_e32 v[6:7], 0
	v_mov_b64_e32 v[8:9], 0
	v_mov_b64_e32 v[10:11], 0
	v_mov_b64_e32 v[12:13], 0
	v_mov_b64_e32 v[14:15], 0
	v_mov_b64_e32 v[16:17], 0
	v_mov_b64_e32 v[18:19], 0
	v_mov_b64_e32 v[20:21], 0
	v_mov_b64_e32 v[22:23], 0
	v_mov_b64_e32 v[24:25], 0
	v_mov_b64_e32 v[26:27], 0
	v_mov_b64_e32 v[28:29], 0
	v_mov_b64_e32 v[30:31], 0
	v_mov_b64_e32 v[32:33], 0
	v_mov_b64_e32 v[34:35], 0
	v_mov_b64_e32 v[36:37], 0
	v_mov_b64_e32 v[38:39], 0
	v_mov_b64_e32 v[40:41], 0
	v_mov_b64_e32 v[42:43], 0
	v_mov_b64_e32 v[44:45], 0
	v_mov_b64_e32 v[46:47], 0
	v_mov_b64_e32 v[48:49], 0
	v_mov_b64_e32 v[50:51], 0
	v_mov_b64_e32 v[52:53], 0
	v_mov_b64_e32 v[54:55], 0
	v_mov_b64_e32 v[56:57], 0
	v_mov_b64_e32 v[58:59], 0
	v_mov_b64_e32 v[60:61], 0
	v_mov_b64_e32 v[62:63], 0
	v_mov_b64_e32 v[64:65], 0
	v_mov_b64_e32 v[66:67], 0
	v_mov_b64_e32 v[68:69], 0
	v_mov_b64_e32 v[70:71], 0
	v_mov_b64_e32 v[72:73], 0
	v_mov_b64_e32 v[74:75], 0
	v_mov_b64_e32 v[76:77], 0
	v_mov_b64_e32 v[78:79], 0
	v_mov_b64_e32 v[80:81], 0
	v_mov_b64_e32 v[82:83], 0
	v_mov_b64_e32 v[84:85], 0
	v_mov_b64_e32 v[86:87], 0
	v_mov_b64_e32 v[88:89], 0
	v_mov_b64_e32 v[90:91], 0
	v_mov_b64_e32 v[92:93], 0
	v_mov_b64_e32 v[94:95], 0
	v_mov_b64_e32 v[96:97], 0
	v_mov_b64_e32 v[98:99], 0
	v_mov_b64_e32 v[100:101], 0
	v_mov_b64_e32 v[102:103], 0
	v_mov_b64_e32 v[104:105], 0
	v_mov_b64_e32 v[106:107], 0
	v_mov_b64_e32 v[108:109], 0
	v_mov_b64_e32 v[110:111], 0
	v_mov_b64_e32 v[112:113], 0
	v_mov_b64_e32 v[114:115], 0
	v_mov_b64_e32 v[116:117], 0
	v_mov_b64_e32 v[118:119], 0
	v_mov_b64_e32 v[120:121], 0
	v_mov_b64_e32 v[122:123], 0
	v_mov_b64_e32 v[124:125], 0
	v_mov_b64_e32 v[126:127], 0

.LBB0_713:
	s_ashr_i32 s51, s50, 31
	s_lshl_b64 s[10:11], s[50:51], 19
	s_add_u32 s52, s15, s10
	s_addc_u32 s53, s16, s11
	s_and_b64 s[10:11], s[40:41], exec
	s_cselect_b32 s24, s53, s7
	s_cselect_b32 s51, s52, s6
	s_ashr_i32 s49, s48, 31
	s_lshl_b64 s[10:11], s[48:49], 19
	s_add_u32 s54, s12, s10
	s_addc_u32 s55, s13, s11
	s_and_b64 s[10:11], s[40:41], exec
	s_cselect_b32 s49, s55, s9
	s_cselect_b32 s56, s54, s8
	s_add_u32 s6, s6, 0x40080
	s_addc_u32 s7, s7, 0
	s_add_u32 s57, s8, 0x100
	v_mov_b32_e32 v0, 0
	s_addc_u32 s58, s9, 0
	s_mov_b32 s59, -2
	v_mov_b32_e32 v1, v0
	v_mov_b64_e32 v[2:3], 0
	v_mov_b64_e32 v[4:5], 0
	v_mov_b64_e32 v[6:7], 0
	v_mov_b64_e32 v[8:9], 0
	v_mov_b64_e32 v[10:11], 0
	v_mov_b64_e32 v[12:13], 0
	v_mov_b64_e32 v[14:15], 0
	v_mov_b64_e32 v[16:17], 0
	v_mov_b64_e32 v[18:19], 0
	v_mov_b64_e32 v[20:21], 0
	v_mov_b64_e32 v[22:23], 0
	v_mov_b64_e32 v[24:25], 0
	v_mov_b64_e32 v[26:27], 0
	v_mov_b64_e32 v[28:29], 0
	v_mov_b64_e32 v[30:31], 0
	v_mov_b64_e32 v[32:33], 0
	v_mov_b64_e32 v[34:35], 0
	v_mov_b64_e32 v[36:37], 0
	v_mov_b64_e32 v[38:39], 0
	v_mov_b64_e32 v[40:41], 0
	v_mov_b64_e32 v[42:43], 0
	v_mov_b64_e32 v[44:45], 0
	v_mov_b64_e32 v[46:47], 0
	v_mov_b64_e32 v[48:49], 0
	v_mov_b64_e32 v[50:51], 0
	v_mov_b64_e32 v[52:53], 0
	v_mov_b64_e32 v[54:55], 0
	v_mov_b64_e32 v[56:57], 0
	v_mov_b64_e32 v[58:59], 0
	v_mov_b64_e32 v[60:61], 0
	v_mov_b64_e32 v[62:63], 0
	v_mov_b64_e32 v[64:65], 0
	v_mov_b64_e32 v[66:67], 0
	v_mov_b64_e32 v[68:69], 0
	v_mov_b64_e32 v[70:71], 0
	v_mov_b64_e32 v[72:73], 0
	v_mov_b64_e32 v[74:75], 0
	v_mov_b64_e32 v[76:77], 0
	v_mov_b64_e32 v[78:79], 0
	v_mov_b64_e32 v[80:81], 0
	v_mov_b64_e32 v[82:83], 0
	v_mov_b64_e32 v[84:85], 0
	v_mov_b64_e32 v[86:87], 0
	v_mov_b64_e32 v[88:89], 0
	v_mov_b64_e32 v[90:91], 0
	v_mov_b64_e32 v[92:93], 0
	v_mov_b64_e32 v[94:95], 0
	v_mov_b64_e32 v[96:97], 0
	v_mov_b64_e32 v[98:99], 0
	v_mov_b64_e32 v[100:101], 0
	v_mov_b64_e32 v[102:103], 0
	v_mov_b64_e32 v[104:105], 0
	v_mov_b64_e32 v[106:107], 0
	v_mov_b64_e32 v[108:109], 0
	v_mov_b64_e32 v[110:111], 0
	v_mov_b64_e32 v[112:113], 0
	v_mov_b64_e32 v[114:115], 0
	v_mov_b64_e32 v[116:117], 0
	v_mov_b64_e32 v[118:119], 0
	v_mov_b64_e32 v[120:121], 0
	v_mov_b64_e32 v[122:123], 0
	v_mov_b64_e32 v[124:125], 0
	v_mov_b64_e32 v[126:127], 0
